# v19 plus one static s_setprio 1 for waves 4-7 at start of attention phases 2 and 10
# speedup vs baseline: 1.0020x; 1.0020x over previous
; #define IN(k) (PH_EN(k) && lo <= (k) && (k) < hi)
;     const bf16_t* QK = (const bf16_t*)(p.ws + WS_BIG); const bf16_t* VT = (const bf16_t*)(p.ws + WS_VT); bf16_t* O = (bf16_t*)(p.ws + WS_XN);
;     const float d1 = wave_sum(p.in[5][lane] * p.in[6][lane]), d2 = wave_sum(p.in[7][lane] * p.in[8][lane]);
;     const float lam = expf(d1) - expf(d2) + 0.2f;
;     {
;         unsigned* qctr = (unsigned*)(p.ws + WS_QCTR) + rep;
;         volatile unsigned* qidx = (volatile unsigned*)(lds + DF_QIDX);
;         for (;;) {
;             if (threadIdx.x == 0) qidx[0] = atomicAdd(qctr, 1u);
;             __syncthreads();
;             const unsigned idx = qidx[0];
;             __syncthreads();
;             if (idx >= 1024u) break;
;             const int bh = idx & 15, qt = 63 - (int)(idx >> 4);
;             diff_block(QK, VT, O, p.in[9], (const unsigned*)(p.ws + WS_KMX), lam, bh >> 2, bh & 3, qt * 128, wave, lane, lds);
; __global__ void __launch_bounds__(512) trunk_fwd(Params p) {
;     ...
;     if (IN(2)) {
; #pragma nounroll
;         for (int rep = 0; rep < (PROBE_DUP == 2 ? 2 : 1); ++rep) phase_attn0(p, lds, wave, lane, rep);
.LBB0_302:
	s_add_u32 s58, s80, 0x3400000
	s_addc_u32 s59, s81, 0
	s_cmp_gt_i32 s82, 2
	s_cselect_b64 s[0:1], -1, 0
	s_cmp_lt_i32 s83, 3
	s_cselect_b64 s[2:3], -1, 0
	s_or_b64 s[0:1], s[0:1], s[2:3]
	s_and_b64 vcc, exec, s[0:1]
	s_cbranch_vccnz .LBB0_410
	v_readfirstlane_b32 s32, v177
	s_nop 3
	s_lshr_b32 s32, s32, 6
	s_cmp_ge_u32 s32, 4
	s_cbranch_scc0 .Lprio_p2_done
	s_setprio 1
.Lprio_p2_done:
	v_readlane_b32 s16, v247, 15
	v_readlane_b32 s17, v247, 16
	v_readlane_b32 s18, v247, 17
	v_readlane_b32 s19, v247, 18
	v_readlane_b32 s28, v247, 27
	v_readlane_b32 s29, v247, 28
	v_lshlrev_b32_e32 v3, 2, v176
	v_readlane_b32 s26, v247, 25
	v_readlane_b32 s27, v247, 26
	v_readlane_b32 s30, v247, 29
	v_readlane_b32 s31, v247, 30
	s_mov_b64 s[16:17], s[28:29]
	s_mov_b64 s[18:19], s[30:31]
	s_nop 0
	global_load_dword v5, v3, s[26:27]
	global_load_dword v6, v3, s[16:17]
	global_load_dword v7, v3, s[18:19]
	global_load_dword v8, v3, s[60:61]
	v_mbcnt_lo_u32_b32 v0, -1, 0
	v_lshrrev_b32_e32 v9, 5, v176
	v_mbcnt_hi_u32_b32 v12, -1, v0
	s_mov_b64 s[14:15], s[26:27]
	v_lshrrev_b32_e32 v10, 1, v177
	v_lshlrev_b32_e32 v0, 4, v9
	v_lshlrev_b32_e32 v146, 3, v9
	v_lshlrev_b32_e32 v144, 2, v9
	v_and_b32_e32 v9, 64, v12
	s_add_u32 s14, s80, 0x31ff600
	v_readlane_b32 s10, v247, 9
	v_and_b32_e32 v165, 4, v10
	v_xor_b32_e32 v10, 1, v12
	v_add_u32_e32 v9, 64, v9
	s_addc_u32 s15, s81, 0
	s_bfe_u32 s8, s10, 0x20006
	v_xor_b32_e32 v13, 2, v12
	v_cmp_lt_i32_e32 vcc, v10, v9
	s_lshl_b32 s42, s8, 5
	s_lshl_b32 s8, s8, 14
	v_cndmask_b32_e32 v10, v12, v10, vcc
	v_cmp_lt_i32_e32 vcc, v13, v9
	s_add_i32 s8, s8, 0
	v_add_u32_e32 v169, s8, v3
	v_cndmask_b32_e32 v13, v12, v13, vcc
	v_lshlrev_b32_e32 v3, 2, v10
	v_lshlrev_b32_e32 v10, 2, v13
	v_lshlrev_b32_e32 v2, 1, v177
	s_and_b32 s7, s10, 0xffffffc0
	s_lshr_b32 s33, s10, 8
	v_and_b32_e32 v163, 19, v177
	v_and_b32_e32 v164, 8, v2
	v_or_b32_e32 v18, s7, v176
	s_mul_i32 s7, s33, 0x1200
	s_movk_i32 s1, 0x90
	v_or3_b32 v19, v164, v163, v165
	v_or_b32_e32 v22, s7, v0
	v_mad_u32_u24 v167, v19, s1, v22
	v_xor_b32_e32 v14, 4, v12
	v_cmp_lt_i32_e32 vcc, v14, v9
	v_xor_b32_e32 v15, 8, v12
	v_xor_b32_e32 v16, 16, v12
	v_cndmask_b32_e32 v14, v12, v14, vcc
	v_lshlrev_b32_e32 v14, 2, v14
	v_cmp_lt_i32_e32 vcc, v15, v9
	v_xor_b32_e32 v17, 32, v12
	v_ashrrev_i32_e32 v21, 2, v18
	v_cndmask_b32_e32 v15, v12, v15, vcc
	v_lshlrev_b32_e32 v15, 2, v15
	v_cmp_lt_i32_e32 vcc, v16, v9
	v_and_b32_e32 v11, 3, v177
	s_mov_b32 s2, 0x3fb8aa3b
	v_cndmask_b32_e32 v16, v12, v16, vcc
	v_lshlrev_b32_e32 v16, 2, v16
	v_cmp_lt_i32_e32 vcc, v17, v9
	s_mov_b32 s3, 0xc2ce8ed0
	v_readlane_b32 s16, v247, 31
	v_cndmask_b32_e32 v9, v12, v17, vcc
	v_lshrrev_b32_e32 v12, 3, v21
	v_lshlrev_b32_e32 v17, 3, v21
	v_lshlrev_b32_e32 v147, 2, v9
	v_and_b32_e32 v9, 0xf8, v17
	s_mov_b32 s6, 0x42b17218
	s_lshl_b32 s9, s16, 2
	s_add_i32 s43, s9, 0
	s_add_i32 s43, s43, 0x13000
	v_and_b32_e32 v145, 31, v177
	v_and_b32_e32 v4, 7, v177
	v_mov_b32_e32 v1, 0
	s_movk_i32 s0, 0x50
	v_readlane_b32 s17, v247, 32
	s_cmp_eq_u32 s33, 1
	v_readlane_b32 s20, v247, 19
	v_readlane_b32 s21, v247, 20
	v_readlane_b32 s22, v247, 21
	v_lshlrev_b32_e32 v2, 3, v4
	v_lshlrev_b32_e32 v4, 4, v4
	s_waitcnt vmcnt(2)
	v_mul_f32_e32 v13, v5, v6
	ds_bpermute_b32 v13, v3, v13
	s_waitcnt vmcnt(0)
	v_mul_f32_e32 v19, v7, v8
	ds_bpermute_b32 v3, v3, v19
	v_lshl_add_u64 v[148:149], s[62:63], 0, v[0:1]
	s_cselect_b64 s[16:17], -1, 0
	s_waitcnt lgkmcnt(1)
	v_fmac_f32_e32 v13, v5, v6
	ds_bpermute_b32 v5, v10, v13
	s_waitcnt lgkmcnt(1)
	v_fmac_f32_e32 v3, v7, v8
	ds_bpermute_b32 v6, v10, v3
	v_and_or_b32 v8, v12, 4, v11
	s_cmpk_lt_u32 s10, 0x100
	s_waitcnt lgkmcnt(1)
	v_add_f32_e32 v5, v13, v5
	ds_bpermute_b32 v7, v14, v5
	s_waitcnt lgkmcnt(1)
	v_add_f32_e32 v3, v3, v6
	ds_bpermute_b32 v6, v14, v3
	v_mad_u32_u24 v172, v145, s0, v0
	v_lshlrev_b32_e32 v0, 8, v18
	s_waitcnt lgkmcnt(1)
	v_add_f32_e32 v5, v5, v7
	ds_bpermute_b32 v7, v15, v5
	s_waitcnt lgkmcnt(1)
	v_add_f32_e32 v3, v3, v6
	ds_bpermute_b32 v10, v15, v3
	v_lshl_or_b32 v6, v8, 8, v9
	s_mov_b64 s[12:13], src_shared_base
	s_waitcnt lgkmcnt(1)
	v_add_f32_e32 v5, v5, v7
	ds_bpermute_b32 v7, v16, v5
	s_waitcnt lgkmcnt(1)
	v_add_f32_e32 v3, v3, v10
	ds_bpermute_b32 v8, v16, v3
	v_readlane_b32 s23, v247, 22
	v_readlane_b32 s24, v247, 23
	s_waitcnt lgkmcnt(1)
	v_add_f32_e32 v5, v5, v7
	ds_bpermute_b32 v7, v147, v5
	s_waitcnt lgkmcnt(1)
	v_add_f32_e32 v3, v3, v8
	ds_bpermute_b32 v8, v147, v3
	v_readlane_b32 s25, v247, 24
	v_bfe_u32 v166, v18, 3, 5
	s_waitcnt lgkmcnt(1)
	v_add_f32_e32 v5, v5, v7
	v_mul_f32_e32 v7, 0x3fb8aa3b, v5
	v_fma_f32 v9, v5, s2, -v7
	v_rndne_f32_e32 v10, v7
	v_fmac_f32_e32 v9, 0x32a5705f, v5
	v_sub_f32_e32 v7, v7, v10
	v_add_f32_e32 v7, v7, v9
	v_cvt_i32_f32_e32 v10, v10
	v_exp_f32_e32 v7, v7
	s_waitcnt lgkmcnt(0)
	v_add_f32_e32 v3, v3, v8
	v_mul_f32_e32 v8, 0x3fb8aa3b, v3
	v_fma_f32 v9, v3, s2, -v8
	v_ldexp_f32 v7, v7, v10
	v_rndne_f32_e32 v10, v8
	v_fmac_f32_e32 v9, 0x32a5705f, v3
	v_sub_f32_e32 v8, v8, v10
	v_add_f32_e32 v8, v8, v9
	v_exp_f32_e32 v8, v8
	v_cvt_i32_f32_e32 v9, v10
	v_cmp_ngt_f32_e32 vcc, s3, v5
	v_mov_b32_e32 v10, 0x7f800000
	v_or_b32_e32 v20, s7, v4
	v_cndmask_b32_e32 v7, 0, v7, vcc
	v_cmp_nlt_f32_e32 vcc, s6, v5
	v_mul_lo_u32 v21, v21, s0
	s_cselect_b64 s[20:21], -1, 0
	v_cndmask_b32_e32 v5, v10, v7, vcc
	v_ldexp_f32 v7, v8, v9
	v_cmp_ngt_f32_e32 vcc, s3, v3
	s_add_u32 s22, s80, 0x31fb000
	v_or_b32_e32 v173, s42, v145
	v_cndmask_b32_e32 v7, 0, v7, vcc
	v_cmp_nlt_f32_e32 vcc, s6, v3
	v_and_b32_e32 v0, 0xf800, v0
	s_mov_b32 s26, 2.0
	v_cndmask_b32_e32 v3, v10, v7, vcc
	v_sub_f32_e32 v3, v5, v3
	v_mov_b32_e32 v5, v1
	s_mov_b32 s28, 4.0
	s_mov_b32 s30, 0x40c00000
	s_mov_b32 s34, 0x41800000
	s_mov_b32 s36, 0x41900000
	s_mov_b32 s46, 0x41a00000
	s_mov_b32 s48, 0x41b00000
	v_cmp_eq_u32_e64 s[4:5], 0, v176
	v_mad_u32_u24 v168, v166, s1, v20
	v_lshl_add_u32 v170, v11, 4, v21
	s_addc_u32 s23, s81, 0
	v_add_f32_e32 v171, 0x3e4ccccd, v3
	v_sub_u32_e32 v174, v173, v146
	v_lshl_add_u64 v[150:151], s[80:81], 0, v[4:5]
	s_mov_b64 s[24:25], 0
	s_movk_i32 s65, 0x400
	v_lshlrev_b32_e32 v152, 1, v2
	v_lshlrev_b32_e32 v154, 1, v6
	s_mov_b32 s66, 0xf800000
	v_mov_b32_e32 v175, 0x260
	s_mov_b32 s12, 0x3e38aa3b
	v_lshlrev_b32_e32 v178, 1, v0
	s_mov_b32 s27, 0x40400000
	s_mov_b32 s29, 0x40a00000
	s_mov_b32 s31, 0x40e00000
	s_mov_b32 s35, 0x41880000
	s_mov_b32 s37, 0x41980000
	s_mov_b32 s47, 0x41a80000
	s_mov_b32 s49, 0x41b80000
	s_mov_b32 s67, 0xf149f2ca
	s_mov_b32 s68, 0x41000000
	s_mov_b32 s69, 0xc3160000
	s_mov_b32 s70, 0xfffc0000
	v_mov_b32_e32 v179, 0x358637bd
	s_mov_b32 s71, 0x800000
	v_mov_b32_e32 v180, 0xff800000
	s_branch .LBB0_306

; DI void nsa_block(const bf16_t* P1, const bf16_t* VT1, const bf16_t* KSF, const bf16_t* KC, const bf16_t* VCT, bf16_t* O, const unsigned* kmx, int b, int g, int t0b, int wave, int lane, unsigned char* lds) {
;     unsigned char* wl = lds + wave * WAVE_LDS; unsigned char* SB = lds + NS_BASE;
;     const int t0w = t0b + 8 * wave, tid = wave * 64 + lane;
;     const bool kst = wave < 4;
;     const int st_row = kst ? (tid >> 3) : ((tid - 256) >> 2), st_ch = kst ? (tid & 7) : ((tid - 256) & 3);
;     const int st_dst = kst ? st_row * 144 + st_ch * 16 : NS_VOFF + st_row * 80 + st_ch * 16;
;     u32x4 sreg = {0u, 0u, 0u, 0u};
;     float* impA = (float*)wl; float* impB = impA + 1024; unsigned long long* selm = (unsigned long long*)(wl + 8192);
;     const int r = lane & 31, hf = lane >> 5, tk = r >> 2, hh = r & 3, krow = krow_of(r);
;     const int t = t0w + tk, head = g * 4 + hh, tmax = t0w + 7;
;     const float slope2 = exp2f(-0.5f * (float)(head + 1)) * LOG2E;
;     const bf16_t* P1 = (const bf16_t*)(p.ws + WS_BIG); const bf16_t* VT1 = (const bf16_t*)(p.ws + WS_VT);
;     const bf16_t* KC = (const bf16_t*)(p.ws + WS_KC); const bf16_t* VCT = (const bf16_t*)(p.ws + WS_VCT); bf16_t* O = (bf16_t*)(p.ws + WS_XN);
;     unsigned* qctr = (unsigned*)(p.ws + WS_QCTR) + 8 + rep;
;     volatile unsigned* qidx = (volatile unsigned*)(lds + NS_BASE + 2 * NS_BUF);
;     for (;;) {
;         if (threadIdx.x == 0) qidx[0] = atomicAdd(qctr, 1u);
;         __syncthreads();
;         const unsigned idx = qidx[0];
;         __syncthreads();
;         if (idx >= 2048u) break;
;         const int bg = idx & 15, tile = 127 - (int)(idx >> 4);
;         nsa_block(P1, VT1, (const bf16_t*)(p.ws + WS_KSF), KC, VCT, O, (const unsigned*)(p.ws + WS_KMX), bg >> 2, bg & 3, tile * 64, wave, lane, lds);
.LBB0_962:
	s_cmp_gt_i32 s82, 10
	s_cselect_b64 s[0:1], -1, 0
	s_cmp_lt_i32 s83, 11
	s_cselect_b64 s[2:3], -1, 0
	s_or_b64 s[0:1], s[0:1], s[2:3]
	s_and_b64 vcc, exec, s[0:1]
	s_cbranch_vccnz .LBB0_1134
	v_readfirstlane_b32 s32, v177
	s_nop 3
	s_lshr_b32 s32, s32, 6
	s_cmp_ge_u32 s32, 4
	s_cbranch_scc0 .Lprio_p10_done
	s_setprio 1
.Lprio_p10_done:
	s_add_u32 s0, s80, 0x3200000
	s_addc_u32 s1, s81, 0
	v_writelane_b32 v246, s0, 37
	s_mov_b64 s[22:23], src_shared_base
	v_and_b32_e32 v141, 3, v177
	v_writelane_b32 v246, s1, 38
	s_add_u32 s0, s80, 0x3300000
	s_addc_u32 s1, s81, 0
	v_writelane_b32 v246, s0, 41
	v_lshlrev_b32_e32 v2, 4, v141
	s_movk_i32 s96, 0x1200
	v_writelane_b32 v246, s1, 42
	s_add_u32 s0, s80, 0x31ff620
	s_addc_u32 s1, s81, 0
	v_writelane_b32 v246, s0, 43
	v_lshlrev_b32_e32 v3, 1, v177
	v_lshrrev_b32_e32 v6, 1, v177
	v_writelane_b32 v246, s1, 44
	v_readlane_b32 s0, v247, 31
	v_readlane_b32 s1, v247, 32
	s_mov_b32 s2, s0
	s_mulk_i32 s0, 0x2200
	v_readlane_b32 s1, v247, 9
	s_add_i32 s51, s0, 0
	s_lshl_b32 s3, s2, 3
	s_and_b32 s0, s1, 0xffffffc0
	s_cmpk_gt_u32 s1, 0xff
	s_cselect_b64 s[34:35], -1, 0
	s_add_u32 s36, s80, 0x31fb180
	v_or_b32_e32 v0, s0, v176
	s_addc_u32 s37, s81, 0
	s_lshl_b32 s0, s2, 2
	s_add_i32 s0, s0, 0
	s_add_i32 s22, s0, 0x15c40
	s_add_i32 s95, 0, 0x11000
	v_ashrrev_i32_e32 v137, 3, v0
	v_add_u32_e32 v0, 0xffffff00, v0
	s_cmpk_lt_u32 s1, 0x100
	v_ashrrev_i32_e32 v4, 2, v0
	s_movk_i32 s1, 0x50
	s_waitcnt lgkmcnt(0)
	v_mul_lo_u32 v1, v4, s1
	s_movk_i32 s1, 0x90
	v_and_b32_e32 v0, 7, v177
	v_add3_u32 v1, v1, v2, s96
	v_mul_lo_u32 v2, v137, s1
	v_and_b32_e32 v3, 8, v3
	v_and_b32_e32 v7, 19, v177
	v_and_b32_e32 v6, 4, v6
	s_cselect_b64 s[8:9], -1, 0
	v_lshl_add_u32 v143, v0, 4, v2
	v_and_b32_e32 v2, 31, v177
	v_mov_b32_e32 v135, 0
	v_or3_b32 v3, v3, v7, v6
	s_and_b64 s[0:1], s[8:9], exec
	v_lshlrev_b32_e32 v134, 4, v176
	v_mul_u32_u24_e32 v174, 0x90, v3
	v_mul_u32_u24_e32 v180, 0x50, v2
	v_lshl_add_u64 v[2:3], s[80:81], 0, v[134:135]
	s_mov_b64 s[0:1], 0x1b700000
	v_lshl_add_u64 v[144:145], v[2:3], 0, s[0:1]
	v_lshrrev_b32_e32 v2, 3, v4
	s_mov_b32 s0, 0xfffffc
	v_lshlrev_b32_e32 v3, 3, v4
	v_lshrrev_b32_e32 v5, 5, v176
	v_bfe_u32 v170, v177, 2, 3
	v_lshlrev_b32_e32 v136, 3, v0
	v_cndmask_b32_e64 v7, v1, v143, s[8:9]
	v_lshlrev_b64 v[0:1], v176, -1
	v_and_or_b32 v2, v2, s0, v141
	v_and_b32_e32 v3, 0xf8, v3
	v_lshlrev_b32_e32 v132, 3, v5
	v_mov_b32_e32 v8, 0xf00
	v_lshlrev_b32_e32 v179, 7, v5
	v_not_b32_e32 v133, v1
	v_lshlrev_b32_e32 v1, 4, v170
	v_lshl_or_b32 v146, v2, 8, v3
	v_or_b32_e32 v3, s3, v170
	v_lshl_or_b32 v8, v177, 2, v8
	v_lshlrev_b32_e32 v175, 4, v5
	v_lshlrev_b32_e32 v138, 5, v4
	v_lshlrev_b32_e32 v6, 1, v5
	s_cselect_b32 s97, 7, 12
	v_not_b32_e32 v142, v0
	s_add_u32 s46, s80, 0x31fb100
	v_lshlrev_b32_e32 v0, 3, v176
	v_lshlrev_b32_e32 v2, 2, v5
	v_sub_u32_e32 v4, v3, v179
	v_sub_u32_e32 v3, v3, v132
	s_mov_b32 s54, 2.0
	v_add_u32_e32 v189, s51, v1
	s_mov_b32 s60, 4.0
	s_mov_b32 s62, 0x40c00000
	s_mov_b32 s64, 0x41800000
	s_mov_b32 s66, 0x41900000
	s_mov_b32 s68, 0x41a00000
	s_mov_b32 s82, 0x41b00000
	v_mbcnt_lo_u32_b32 v1, -1, 0
	s_mov_b32 s31, 0
	v_lshl_add_u32 v171, v176, 2, s51
	v_or_b32_e32 v172, 64, v176
	v_add_u32_e32 v173, s51, v8
	v_cmp_eq_u32_e64 s[4:5], 0, v176
	v_add3_u32 v178, s95, v174, v175
	v_ashrrev_i32_e32 v139, 31, v138
	v_lshlrev_b32_e32 v140, 3, v141
	v_cmp_eq_u32_e64 s[6:7], 0, v141
	s_addc_u32 s47, s81, 0
	v_ashrrev_i32_e32 v147, 31, v146
	v_add_u32_e32 v181, s95, v7
	v_add_u32_e32 v182, 0xfffffe71, v4
	v_add_u32_e32 v183, 32, v137
	v_lshl_or_b32 v184, v170, 7, v6
	v_xor_b32_e32 v185, 0x7a, v6
	s_add_i32 s33, s51, 0x2000
	v_subrev_u32_e32 v186, 33, v3
	s_mov_b64 s[48:49], 0
	s_add_i32 s26, 0, 0x15c00
	s_mov_b32 s30, 0xf800000
	v_mov_b32_e32 v187, 0x260
	s_mov_b32 s50, 0x3e38aa3b
	s_mov_b32 s53, 0x3fb8aa3b
	s_mov_b32 s55, 0x40400000
	v_mov_b32_e32 v188, 0xc1f80000
	s_movk_i32 s28, 0x200
	s_mov_b32 s61, 0x40a00000
	s_mov_b32 s63, 0x40e00000
	s_mov_b32 s65, 0x41880000
	s_mov_b32 s67, 0x41980000
	s_mov_b32 s69, 0x41a80000
	s_mov_b32 s83, 0x41b80000
	s_mov_b32 s29, 0xf149f2ca
	s_mov_b32 s27, 0x41000000
	s_mov_b64 s[84:85], 0xe00
	v_lshlrev_b32_e32 v148, 1, v2
	v_mov_b32_e32 v190, 0x42800000
	v_not_b32_e32 v191, 63
	v_mbcnt_hi_u32_b32 v192, -1, v1
	v_mov_b32_e32 v193, 0x2600
	v_mov_b32_e32 v150, 0x3e38aa3b
	v_mov_b32_e32 v194, 0xff800000
	v_lshlrev_b32_e32 v152, 1, v0
	v_mov_b32_e32 v154, 1.0
	v_writelane_b32 v246, s3, 39
	s_branch .LBB0_967
